# attention: queue pop + norm weights hoisted, epilogue re-emitted (batched LDS, paired rows, 32 full-wave stores); GDN scan: output section beside the state-update MFMAs, silu(z) gate beside the MFMAs
# speedup vs baseline: 1.0091x; 1.0031x over previous
.LBB0_706:
	v_lshlrev_b32_e32 v0, 2, v134
	v_add_u32_e32 v0, 0x1a000, v0
	ds_read_b32 v96, v0
	ds_read_b32 v97, v0 offset:2048
	ds_read_b32 v98, v0 offset:4096
	ds_read_b32 v99, v0 offset:6144
	ds_read_b32 v100, v0 offset:8192
	ds_read_b32 v101, v0 offset:10240
	ds_read_b32 v102, v0 offset:12288
	ds_read_b32 v108, v0 offset:14336
	ds_read_b32 v109, v0 offset:16384
	ds_read_b32 v110, v0 offset:18432
	ds_read_b32 v111, v0 offset:20480
	ds_read_b32 v112, v0 offset:22528
	ds_read_b32 v113, v0 offset:24576
	ds_read_b32 v114, v0 offset:26624
	ds_read_b32 v115, v0 offset:28672
	ds_read_b32 v116, v0 offset:30720
	ds_read_b32 v117, v0 offset:32768
	s_waitcnt lgkmcnt(0)
	s_add_i32 s16, s16, s94
	s_add_i32 s14, s14, s62
	s_cmp_gt_i32 s16, 63
	s_cbranch_scc1 .LBB0_721
.LBB0_707:
	s_bfe_u32 s0, s14, 0x30003
	s_lshl_b32 s17, s0, 8
	s_lshl_b32 s20, s0, 3
	s_lshl_b32 s0, s16, 3
	s_and_b32 s0, s0, 56
	s_ashr_i32 s21, s16, 3
	s_add_i32 s10, s0, s21
	s_ashr_i32 s8, s10, 2
	s_ashr_i32 s11, s10, 31
	s_lshl_b64 s[18:19], s[10:11], 18
	v_lshlrev_b64 v[0:1], 7, v[96:97]
	s_ashr_i32 s9, s8, 31
	v_readfirstlane_b32 s22, v134
	v_lshl_add_u64 v[0:1], s[18:19], 0, v[0:1]
	s_lshl_b64 s[18:19], s[8:9], 11
	s_ashr_i32 s0, s22, 2
	v_lshl_add_u64 v[2:3], s[18:19], 0, v[96:97]
	v_mov_b64_e32 v[4:5], s[74:75]
	v_mad_u64_u32 v[4:5], s[18:19], v2, s15, v[4:5]
	s_lshl_b32 s10, s10, 5
	v_and_or_b32 v40, s0, -16, v101
	s_lshl_b32 s0, s21, 8
	v_mad_i32_i24 v5, v3, s15, v5
	s_ashr_i32 s11, s10, 31
	v_readlane_b32 s36, v254, 12
	s_and_b32 s0, s0, 0x300
	v_ashrrev_i32_e32 v41, 31, v40
	v_readlane_b32 s48, v254, 24
	v_readlane_b32 s49, v254, 25
	v_lshlrev_b64 v[0:1], 1, v[0:1]
	v_lshl_add_u64 v[32:33], v[4:5], 0, s[0:1]
	s_lshl_b64 s[10:11], s[10:11], 2
	v_lshlrev_b32_e32 v34, 1, v100
	v_mov_b32_e32 v35, v103
	v_lshl_add_u64 v[2:3], v[40:41], 2, s[48:49]
	v_lshl_add_u64 v[6:7], v[198:199], 0, v[0:1]
	v_lshl_add_u64 v[12:13], v[98:99], 0, v[0:1]
	v_lshl_add_u64 v[20:21], v[108:109], 0, v[0:1]
	s_add_u32 s10, s12, s10
	v_lshl_add_u64 v[28:29], v[32:33], 0, v[102:103]
	v_lshl_add_u64 v[36:37], v[32:33], 0, v[34:35]
	global_load_dword v168, v[2:3], off
	s_addc_u32 s11, s13, s11
	global_load_dwordx4 v[0:3], v[6:7], off
	s_nop 0
	global_load_dwordx4 v[4:7], v[6:7], off offset:16
	s_nop 0
	global_load_dwordx4 v[8:11], v[12:13], off
	s_nop 0
	global_load_dwordx4 v[12:15], v[12:13], off offset:16
	s_nop 0
	global_load_dwordx4 v[16:19], v[20:21], off
	s_nop 0
	global_load_dwordx4 v[20:23], v[20:21], off offset:16
	s_nop 0
	global_load_dwordx4 v[24:27], v[28:29], off offset:1152
	s_nop 0
	global_load_dwordx4 v[28:31], v[28:29], off offset:1280
	s_nop 0
	global_load_dwordx4 v[32:35], v[36:37], off offset:2176
	s_nop 0
	global_load_dwordx4 v[36:39], v[36:37], off offset:2192
	s_nop 0
	global_load_dword v118, v103, s[10:11]
	s_and_b32 s10, s22, 0x3fffffc0
	v_lshl_add_u32 v169, s10, 2, v136
	s_lshl_b32 s10, s21, 5
	s_add_i32 s10, s17, s10
	s_ashr_i32 s11, s10, 31
	s_lshl_b64 s[10:11], s[10:11], 2
	s_add_u32 s17, s10, 0x1f00004
	s_addc_u32 s18, s11, 0
	s_lshl_b64 s[10:11], s[8:9], 22
	s_or_b32 s10, s10, s0
	v_lshl_add_u64 v[120:121], s[10:11], 0, v[110:111]
	s_add_i32 s10, s21, s20
	s_mul_hi_i32 s9, s8, 0xb00000
	s_mul_i32 s8, s8, 0xb00000
	s_ashr_i32 s11, s10, 31
	v_lshlrev_b32_e32 v40, 1, v40
	s_or_b32 s8, s8, s0
	s_lshl_b64 s[10:11], s[10:11], 19
	v_lshl_add_u64 v[122:123], s[8:9], 0, v[114:115]
	v_lshl_add_u64 v[124:125], v[116:117], 0, s[10:11]
	v_lshl_add_u64 v[126:127], s[8:9], 0, v[112:113]
	v_lshl_add_u64 v[72:73], s[92:93], 0, v[122:123]
	s_mov_b64 s[10:11], 0x2001000
	v_lshl_add_u64 v[72:73], v[72:73], 0, s[10:11]
	global_load_dwordx4 v[76:79], v[72:73], off offset:128
	global_load_dwordx4 v[72:75], v[72:73], off offset:144
	s_mov_b32 s0, 32
	v_add_u32_e32 v170, v159, v40
	v_add_u32_e32 v171, v160, v40
	v_mov_b32_e32 v40, 0
	v_mov_b32_e32 v41, v103
	v_mov_b32_e32 v42, v103
	v_mov_b32_e32 v43, v103
	v_mov_b32_e32 v44, 0
	v_mov_b32_e32 v45, v103
	v_mov_b32_e32 v46, v103
	v_mov_b32_e32 v47, v103
	v_mov_b32_e32 v48, 0
	v_mov_b32_e32 v49, v103
	v_mov_b32_e32 v50, v103
	v_mov_b32_e32 v51, v103
	v_mov_b32_e32 v52, 0
	v_mov_b32_e32 v53, v103
	v_mov_b32_e32 v54, v103
	v_mov_b32_e32 v55, v103
	v_mov_b32_e32 v60, 0
	v_mov_b32_e32 v61, v103
	v_mov_b32_e32 v62, v103
	v_mov_b32_e32 v63, v103
	v_mov_b32_e32 v56, 0
	v_mov_b32_e32 v57, v103
	v_mov_b32_e32 v58, v103
	v_mov_b32_e32 v59, v103
	v_mov_b32_e32 v64, 0
	v_mov_b32_e32 v65, v103
	v_mov_b32_e32 v66, v103
	v_mov_b32_e32 v67, v103
	v_mov_b32_e32 v68, 0
	v_mov_b32_e32 v69, v103
	v_mov_b32_e32 v70, v103
	v_mov_b32_e32 v71, v103
	v_readlane_b32 s37, v254, 13
	v_readlane_b32 s38, v254, 14
	v_readlane_b32 s39, v254, 15
	v_readlane_b32 s40, v254, 16
	v_readlane_b32 s41, v254, 17
	v_readlane_b32 s42, v254, 18
	v_readlane_b32 s43, v254, 19
	v_readlane_b32 s44, v254, 20
	v_readlane_b32 s45, v254, 21
	v_readlane_b32 s46, v254, 22
	v_readlane_b32 s47, v254, 23
	v_readlane_b32 s50, v254, 26
	v_readlane_b32 s51, v254, 27
	s_waitcnt vmcnt(12)
	ds_write_b128 v164, v[0:3]
	s_waitcnt vmcnt(11)
	ds_write_b128 v164, v[4:7] offset:16
	s_waitcnt vmcnt(10)
	ds_write_b128 v164, v[8:11] offset:18432
	s_waitcnt vmcnt(9)
	ds_write_b128 v164, v[12:15] offset:18448
	s_waitcnt vmcnt(8)
	ds_write_b128 v164, v[16:19] offset:36864
	s_waitcnt vmcnt(7)
	ds_write_b128 v164, v[20:23] offset:36880
	s_waitcnt vmcnt(4)
	ds_write_b128 v165, v[32:35] offset:55296
	s_waitcnt vmcnt(3)
	ds_write_b128 v165, v[36:39] offset:55312
	ds_write_b128 v166, v[24:27]
	ds_write_b128 v167, v[28:31]
	s_waitcnt vmcnt(0)
	v_mov_b32_e32 v172, v118
	v_lshlrev_b32_e32 v0, 2, v134
	v_add_u32_e32 v0, 0x1a000, v0
	ds_write_b32 v0, v96
	ds_write_b32 v0, v97 offset:2048
	ds_write_b32 v0, v98 offset:4096
	ds_write_b32 v0, v99 offset:6144
	ds_write_b32 v0, v100 offset:8192
	ds_write_b32 v0, v101 offset:10240
	ds_write_b32 v0, v102 offset:12288
	ds_write_b32 v0, v108 offset:14336
	ds_write_b32 v0, v109 offset:16384
	ds_write_b32 v0, v110 offset:18432
	ds_write_b32 v0, v111 offset:20480
	ds_write_b32 v0, v112 offset:22528
	ds_write_b32 v0, v113 offset:24576
	ds_write_b32 v0, v114 offset:26624
	ds_write_b32 v0, v115 offset:28672
	ds_write_b32 v0, v116 offset:30720
	ds_write_b32 v0, v117 offset:32768
	s_waitcnt lgkmcnt(0)
	s_barrier
	s_branch .LBB0_709
.LBB0_708:
	s_waitcnt lgkmcnt(15)
	v_add_f32_e32 v182, 0, v174
	v_add_f32_e32 v183, v182, v175
	s_mov_b32 s8, 0xd000000
	s_add_u32 s17, s17, 4
	s_waitcnt lgkmcnt(14)
	v_add_f32_e32 v182, v183, v176
	v_add_f32_e32 v183, v182, v177
	s_addc_u32 s18, s18, 0
	s_add_i32 s0, s0, -1
	s_waitcnt lgkmcnt(13)
	v_add_f32_e32 v182, v183, v178
	v_add_f32_e32 v183, v182, v179
	v_lshl_add_u64 v[122:123], v[122:123], 0, s[6:7]
	s_waitcnt lgkmcnt(12)
	v_add_f32_e32 v182, v183, v180
	v_add_f32_e32 v182, v182, v181
	v_fmamk_f32 v182, v182, 0x3c000000, v162
	v_rsq_f32_e32 v88, v182
	v_lshl_add_u64 v[126:127], v[126:127], 0, s[6:7]
	s_cmp_lg_u32 s0, 0
	s_waitcnt lgkmcnt(10)
	v_lshlrev_b32_e32 v90, 16, v84
	v_and_b32_e32 v91, 0xffff0000, v84
	v_pk_mul_f32 v[90:91], v[88:89], v[90:91] op_sel_hi:[0,1]
	v_pk_mul_f32 v[90:91], v[96:97], v[90:91]
	v_cvt_pk_bf16_f32 v84, v90, v91
	v_lshlrev_b32_e32 v92, 16, v85
	v_and_b32_e32 v93, 0xffff0000, v85
	v_pk_mul_f32 v[92:93], v[88:89], v[92:93] op_sel_hi:[0,1]
	v_pk_mul_f32 v[92:93], v[98:99], v[92:93]
	v_cvt_pk_bf16_f32 v85, v92, v93
	v_lshlrev_b32_e32 v94, 16, v86
	v_and_b32_e32 v95, 0xffff0000, v86
	v_pk_mul_f32 v[94:95], v[88:89], v[94:95] op_sel_hi:[0,1]
	v_pk_mul_f32 v[94:95], v[100:101], v[94:95]
	v_cvt_pk_bf16_f32 v86, v94, v95
	v_lshlrev_b32_e32 v90, 16, v87
	v_and_b32_e32 v91, 0xffff0000, v87
	v_pk_mul_f32 v[90:91], v[88:89], v[90:91] op_sel_hi:[0,1]
	v_pk_mul_f32 v[90:91], v[108:109], v[90:91]
	v_cvt_pk_bf16_f32 v87, v90, v91
	v_lshl_add_u64 v[182:183], s[92:93], 0, v[120:121]
	v_add_co_u32_e32 v182, vcc, s8, v182
	s_mov_b64 s[8:9], 0x20000
	v_lshl_add_u64 v[120:121], v[120:121], 0, s[8:9]
	s_mov_b64 s[8:9], 0x4000
	v_addc_co_u32_e32 v183, vcc, 0, v183, vcc
	v_lshl_add_u64 v[124:125], v[124:125], 0, s[8:9]
	v_lshlrev_b32_e32 v92, 16, v80
	v_and_b32_e32 v93, 0xffff0000, v80
	v_pk_mul_f32 v[92:93], v[88:89], v[92:93] op_sel_hi:[0,1]
	v_pk_mul_f32 v[92:93], v[110:111], v[92:93]
	v_cvt_pk_bf16_f32 v80, v92, v93
	v_lshlrev_b32_e32 v94, 16, v81
	v_and_b32_e32 v95, 0xffff0000, v81
	v_pk_mul_f32 v[94:95], v[88:89], v[94:95] op_sel_hi:[0,1]
	v_pk_mul_f32 v[94:95], v[112:113], v[94:95]
	v_cvt_pk_bf16_f32 v81, v94, v95
	v_lshlrev_b32_e32 v90, 16, v82
	v_and_b32_e32 v91, 0xffff0000, v82
	v_pk_mul_f32 v[90:91], v[88:89], v[90:91] op_sel_hi:[0,1]
	v_pk_mul_f32 v[90:91], v[114:115], v[90:91]
	v_cvt_pk_bf16_f32 v82, v90, v91
	v_lshlrev_b32_e32 v92, 16, v83
	v_and_b32_e32 v93, 0xffff0000, v83
	v_pk_mul_f32 v[92:93], v[88:89], v[92:93] op_sel_hi:[0,1]
	v_pk_mul_f32 v[92:93], v[116:117], v[92:93]
	v_cvt_pk_bf16_f32 v83, v92, v93
	global_store_dwordx4 v[182:183], v[84:87], off offset:1024
	global_store_dwordx4 v[182:183], v[80:83], off offset:1040
	s_barrier
	s_cbranch_scc0 .LBB0_706
.LBB0_709:
	ds_read_b128 v[128:131], v161 offset:18432
	ds_read_b128 v[174:177], v161 offset:18496
	ds_read_b128 v[178:181], v161 offset:23040
	ds_read_b128 v[182:185], v161 offset:23104
	ds_read_b128 v[186:189], v161 offset:27648
	ds_read_b128 v[190:193], v161 offset:27712
	ds_read_b128 v[194:197], v161 offset:32256
	ds_read_b128 v[202:205], v161 offset:32320
	ds_read_b128 v[206:209], v161 offset:18560
	ds_read_b128 v[210:213], v161 offset:18624
	ds_read_b128 v[214:217], v161 offset:23168
	ds_read_b128 v[218:221], v161 offset:23232
	ds_read_b128 v[222:225], v161 offset:27776
	ds_read_b128 v[226:229], v161 offset:27840
	ds_read_b128 v[230:233], v161 offset:32384
	ds_read_b128 v[234:237], v161 offset:32448
	ds_read_u16 v238, v170 offset:36864
	ds_read_u16 v239, v170 offset:37152
	ds_read_u16 v240, v170 offset:37440
	ds_read_u16 v241, v170 offset:37728
	ds_read_u16 v242, v170 offset:41472
	ds_read_u16 v243, v170 offset:41760
	ds_read_u16 v244, v170 offset:42048
	ds_read_u16 v245, v170 offset:42336
	ds_read_u16 v246, v170 offset:46080
	ds_read_u16 v247, v170 offset:46368
	ds_read_u16 v248, v170 offset:46656
	ds_read_u16 v249, v170 offset:46944
	ds_read_u16 v250, v170 offset:50688
	ds_read_u16 v251, v170 offset:50976
	ds_read_u16 v252, v170 offset:51264
	ds_read_u16 v253, v170 offset:51552
	s_cmp_lg_u32 s0, 1
	s_cselect_b64 s[8:9], -1, 0
	s_cmp_eq_u32 s0, 1
	s_cbranch_scc1 .LBB0_711
	v_lshl_add_u64 v[36:37], s[92:93], 0, v[122:123]
	v_lshl_add_u64 v[16:17], s[92:93], 0, v[124:125]
	v_add_co_u32_e32 v4, vcc, 0x1a004000, v16
	v_lshl_add_u64 v[24:25], s[92:93], 0, v[126:127]
	s_nop 0
	v_addc_co_u32_e32 v5, vcc, 0, v17, vcc
	v_add_co_u32_e32 v12, vcc, 0x1c004000, v16
	s_add_u32 s10, s92, s17
	s_nop 0
	v_addc_co_u32_e32 v13, vcc, 0, v17, vcc
	v_add_co_u32_e32 v20, vcc, 0x1e004000, v16
	s_addc_u32 s11, s93, s18
	s_nop 0
	v_addc_co_u32_e32 v21, vcc, 0, v17, vcc
	v_add_co_u32_e32 v28, vcc, 0x2058000, v24
	global_load_dwordx4 v[0:3], v[4:5], off
	s_nop 0
	global_load_dwordx4 v[4:7], v[4:5], off offset:16
	v_addc_co_u32_e32 v29, vcc, 0, v25, vcc
	v_add_co_u32_e32 v36, vcc, 0x2058000, v36
	global_load_dwordx4 v[8:11], v[12:13], off
	s_nop 0
	global_load_dwordx4 v[12:15], v[12:13], off offset:16
	v_addc_co_u32_e32 v37, vcc, 0, v37, vcc
	global_load_dwordx4 v[16:19], v[20:21], off
	s_nop 0
	global_load_dwordx4 v[20:23], v[20:21], off offset:16
	s_nop 0
	global_load_dwordx4 v[24:27], v[28:29], off offset:1152
	s_nop 0
	global_load_dwordx4 v[28:31], v[28:29], off offset:1280
	s_nop 0
	global_load_dwordx4 v[32:35], v[36:37], off offset:2176
	s_nop 0
	global_load_dwordx4 v[36:39], v[36:37], off offset:2192
	s_nop 0
	global_load_dword v172, v103, s[10:11]
.LBB0_711:
	v_cvt_pk_bf16_f32 v92, v52, v53
	v_cvt_pk_bf16_f32 v93, v54, v55
	v_cvt_pk_bf16_f32 v94, v48, v49
	v_cvt_pk_bf16_f32 v95, v50, v51
	v_cvt_pk_bf16_f32 v88, v44, v45
	v_cvt_pk_bf16_f32 v89, v46, v47
	v_cvt_pk_bf16_f32 v90, v40, v41
	v_cvt_pk_bf16_f32 v91, v42, v43
	v_cvt_pk_bf16_f32 v84, v60, v61
	v_cvt_pk_bf16_f32 v85, v62, v63
	v_cvt_pk_bf16_f32 v86, v56, v57
	v_cvt_pk_bf16_f32 v87, v58, v59
	v_cvt_pk_bf16_f32 v80, v64, v65
	v_cvt_pk_bf16_f32 v81, v66, v67
	v_cvt_pk_bf16_f32 v82, v68, v69
	v_cvt_pk_bf16_f32 v83, v70, v71
	s_waitcnt lgkmcnt(0)
	v_lshlrev_b32_e32 v238, 16, v238
	v_lshlrev_b32_e32 v239, 16, v239
	v_lshlrev_b32_e32 v240, 16, v240
	v_lshlrev_b32_e32 v241, 16, v241
	v_lshlrev_b32_e32 v242, 16, v242
	v_lshlrev_b32_e32 v243, 16, v243
	v_lshlrev_b32_e32 v244, 16, v244
	v_lshlrev_b32_e32 v245, 16, v245
	v_lshlrev_b32_e32 v246, 16, v246
	v_lshlrev_b32_e32 v247, 16, v247
	v_lshlrev_b32_e32 v248, 16, v248
	v_lshlrev_b32_e32 v249, 16, v249
	v_lshlrev_b32_e32 v250, 16, v250
	v_lshlrev_b32_e32 v251, 16, v251
	v_lshlrev_b32_e32 v252, 16, v252
	v_lshlrev_b32_e32 v253, 16, v253
	v_mfma_f32_16x16x32_bf16 v[128:131], v[128:131], v[92:95], v[238:241]
	v_mfma_f32_16x16x32_bf16 v[178:181], v[178:181], v[92:95], v[242:245]
	v_mfma_f32_16x16x32_bf16 v[186:189], v[186:189], v[92:95], v[246:249]
	v_mfma_f32_16x16x32_bf16 v[194:197], v[194:197], v[92:95], v[250:253]
	v_mfma_f32_16x16x32_bf16 v[128:131], v[174:177], v[88:91], v[128:131]
	v_mfma_f32_16x16x32_bf16 v[174:177], v[182:185], v[88:91], v[178:181]
	v_mfma_f32_16x16x32_bf16 v[178:181], v[190:193], v[88:91], v[186:189]
	v_mfma_f32_16x16x32_bf16 v[182:185], v[202:205], v[88:91], v[194:197]
	s_nop 2
	ds_read_b128 v[186:189], v161
	ds_read_b128 v[190:193], v161 offset:64
	ds_read_b128 v[194:197], v161 offset:4608
	ds_read_b128 v[202:205], v161 offset:4672
	ds_read_b128 v[238:241], v161 offset:9216
	ds_read_b128 v[242:245], v161 offset:9280
	ds_read_b128 v[246:249], v161 offset:13824
	ds_read_b128 v[250:253], v161 offset:13888
	v_mfma_f32_16x16x32_bf16 v[128:131], v[206:209], v[84:87], v[128:131]
	s_cmp_lg_u64 s[8:9], 0
	s_cbranch_scc0 .Lscan_zw_last
	s_waitcnt vmcnt(13)
	s_branch .Lscan_zw_done
.Lscan_zw_last:
	s_waitcnt vmcnt(2)
.Lscan_zw_done:
	v_lshlrev_b32_e32 v96, 16, v76
	v_and_b32_e32 v97, 0xffff0000, v76
	v_mul_f32_e32 v76, 0xbfb8aa3b, v96
	v_mfma_f32_16x16x32_bf16 v[174:177], v[214:217], v[84:87], v[174:177]
	v_mul_f32_e32 v102, 0xbfb8aa3b, v97
	v_exp_f32_e32 v76, v76
	v_exp_f32_e32 v102, v102
	v_mfma_f32_16x16x32_bf16 v[178:181], v[222:225], v[84:87], v[178:181]
	v_add_f32_e32 v76, 1.0, v76
	v_add_f32_e32 v102, 1.0, v102
	v_rcp_f32_e32 v76, v76
	v_mfma_f32_16x16x32_bf16 v[182:185], v[230:233], v[84:87], v[182:185]
	v_rcp_f32_e32 v102, v102
	v_mul_f32_e32 v96, v76, v96
	v_mul_f32_e32 v97, v102, v97
	v_mfma_f32_16x16x32_bf16 v[128:131], v[210:213], v[80:83], v[128:131]
	v_lshlrev_b32_e32 v98, 16, v77
	v_and_b32_e32 v99, 0xffff0000, v77
	v_mul_f32_e32 v77, 0xbfb8aa3b, v98
	v_mfma_f32_16x16x32_bf16 v[174:177], v[218:221], v[80:83], v[174:177]
	v_mul_f32_e32 v102, 0xbfb8aa3b, v99
	v_exp_f32_e32 v77, v77
	v_exp_f32_e32 v102, v102
	v_mfma_f32_16x16x32_bf16 v[178:181], v[226:229], v[80:83], v[178:181]
	v_add_f32_e32 v77, 1.0, v77
	v_add_f32_e32 v102, 1.0, v102
	v_rcp_f32_e32 v77, v77
	v_mfma_f32_16x16x32_bf16 v[182:185], v[234:237], v[80:83], v[182:185]
	v_rcp_f32_e32 v102, v102
	v_mul_f32_e32 v98, v77, v98
	v_mul_f32_e32 v99, v102, v99
	ds_read_b128 v[206:209], v161 offset:128
	ds_read_b128 v[210:213], v161 offset:192
	ds_read_b128 v[214:217], v161 offset:4736
	ds_read_b128 v[218:221], v161 offset:4800
	ds_read_b128 v[222:225], v161 offset:9344
	ds_read_b128 v[226:229], v161 offset:9408
	ds_read_b128 v[230:233], v161 offset:13952
	ds_read_b128 v[234:237], v161 offset:14016
	v_cvt_pk_bf16_f32 v128, v128, v129
	v_cvt_pk_bf16_f32 v129, v130, v131
	v_cvt_pk_bf16_f32 v130, v174, v175
	v_cvt_pk_bf16_f32 v131, v176, v177
	v_cvt_pk_bf16_f32 v174, v178, v179
	v_cvt_pk_bf16_f32 v175, v180, v181
	v_cvt_pk_bf16_f32 v176, v182, v183
	v_cvt_pk_bf16_f32 v177, v184, v185
	s_waitcnt lgkmcnt(14)
	v_mfma_f32_16x16x32_bf16 v[178:181], v[186:189], v[92:95], 0
	v_lshlrev_b32_e32 v100, 16, v78
	v_and_b32_e32 v101, 0xffff0000, v78
	v_mul_f32_e32 v78, 0xbfb8aa3b, v100
	s_waitcnt lgkmcnt(13)
	v_mfma_f32_16x16x32_bf16 v[182:185], v[194:197], v[92:95], 0
	v_mul_f32_e32 v102, 0xbfb8aa3b, v101
	v_exp_f32_e32 v78, v78
	v_exp_f32_e32 v102, v102
	s_waitcnt lgkmcnt(11)
	v_mfma_f32_16x16x32_bf16 v[186:189], v[238:241], v[92:95], 0
	v_add_f32_e32 v78, 1.0, v78
	v_add_f32_e32 v102, 1.0, v102
	v_rcp_f32_e32 v78, v78
	s_waitcnt lgkmcnt(9)
	v_mfma_f32_16x16x32_bf16 v[92:95], v[246:249], v[92:95], 0
	v_rcp_f32_e32 v102, v102
	v_mul_f32_e32 v100, v78, v100
	v_mul_f32_e32 v101, v102, v101
	v_mfma_f32_16x16x32_bf16 v[178:181], v[190:193], v[88:91], v[178:181]
	v_lshlrev_b32_e32 v108, 16, v79
	v_and_b32_e32 v109, 0xffff0000, v79
	v_mul_f32_e32 v79, 0xbfb8aa3b, v108
	v_mfma_f32_16x16x32_bf16 v[182:185], v[202:205], v[88:91], v[182:185]
	v_mul_f32_e32 v102, 0xbfb8aa3b, v109
	v_exp_f32_e32 v79, v79
	v_exp_f32_e32 v102, v102
	v_mfma_f32_16x16x32_bf16 v[186:189], v[242:245], v[88:91], v[186:189]
	v_add_f32_e32 v79, 1.0, v79
	v_add_f32_e32 v102, 1.0, v102
	v_rcp_f32_e32 v79, v79
	s_waitcnt lgkmcnt(8)
	v_mfma_f32_16x16x32_bf16 v[88:91], v[250:253], v[88:91], v[92:95]
	v_rcp_f32_e32 v102, v102
	v_mul_f32_e32 v108, v79, v108
	v_mul_f32_e32 v109, v102, v109
	s_nop 2
	ds_read_b128 v[92:95], v132
	ds_read_b128 v[190:193], v138
	ds_read_b128 v[194:197], v139
	ds_read_b128 v[202:205], v140
	ds_read_b128 v[238:241], v141
	ds_read_b128 v[242:245], v142
	ds_read_b128 v[246:249], v143
	ds_read_b128 v[250:253], v144
	s_waitcnt lgkmcnt(14)
	v_mfma_f32_16x16x32_bf16 v[178:181], v[206:209], v[84:87], v[178:181]
	v_lshlrev_b32_e32 v110, 16, v72
	v_and_b32_e32 v111, 0xffff0000, v72
	v_mul_f32_e32 v72, 0xbfb8aa3b, v110
	s_waitcnt lgkmcnt(13)
	v_mfma_f32_16x16x32_bf16 v[182:185], v[214:217], v[84:87], v[182:185]
	v_mul_f32_e32 v102, 0xbfb8aa3b, v111
	v_exp_f32_e32 v72, v72
	v_exp_f32_e32 v102, v102
	s_waitcnt lgkmcnt(11)
	v_mfma_f32_16x16x32_bf16 v[186:189], v[222:225], v[84:87], v[186:189]
	v_add_f32_e32 v72, 1.0, v72
	v_add_f32_e32 v102, 1.0, v102
	v_rcp_f32_e32 v72, v72
	s_waitcnt lgkmcnt(9)
	v_mfma_f32_16x16x32_bf16 v[84:87], v[230:233], v[84:87], v[88:91]
	v_rcp_f32_e32 v102, v102
	v_mul_f32_e32 v110, v72, v110
	v_mul_f32_e32 v111, v102, v111
	v_mfma_f32_16x16x32_bf16 v[88:91], v[210:213], v[80:83], v[178:181]
	v_lshlrev_b32_e32 v112, 16, v73
	v_and_b32_e32 v113, 0xffff0000, v73
	v_mul_f32_e32 v73, 0xbfb8aa3b, v112
	v_mfma_f32_16x16x32_bf16 v[178:181], v[218:221], v[80:83], v[182:185]
	v_mul_f32_e32 v102, 0xbfb8aa3b, v113
	v_exp_f32_e32 v73, v73
	v_exp_f32_e32 v102, v102
	s_nop 2
	ds_read_b128 v[182:185], v133
	ds_read_b128 v[206:209], v145
	ds_read_b128 v[210:213], v146
	ds_read_b128 v[214:217], v147
	v_mfma_f32_16x16x32_bf16 v[186:189], v[226:229], v[80:83], v[186:189]
	v_add_f32_e32 v73, 1.0, v73
	v_add_f32_e32 v102, 1.0, v102
	v_rcp_f32_e32 v73, v73
	ds_read_b128 v[218:221], v148
	ds_read_b128 v[222:225], v149
	ds_read_b128 v[226:229], v150
	ds_read_b128 v[230:233], v151
	s_waitcnt lgkmcnt(14)
	v_mfma_f32_16x16x32_bf16 v[80:83], v[234:237], v[80:83], v[84:87]
	v_rcp_f32_e32 v102, v102
	v_mul_f32_e32 v112, v73, v112
	v_mul_f32_e32 v113, v102, v113
	v_mfma_f32_16x16x32_bf16 v[84:87], v[92:95], v[128:131], 0
	v_lshlrev_b32_e32 v114, 16, v74
	v_and_b32_e32 v115, 0xffff0000, v74
	v_mul_f32_e32 v74, 0xbfb8aa3b, v114
	s_waitcnt lgkmcnt(13)
	v_mfma_f32_16x16x32_bf16 v[92:95], v[194:197], v[128:131], 0
	v_mul_f32_e32 v102, 0xbfb8aa3b, v115
	v_exp_f32_e32 v74, v74
	v_exp_f32_e32 v102, v102
	s_waitcnt lgkmcnt(11)
	v_mfma_f32_16x16x32_bf16 v[194:197], v[238:241], v[128:131], 0
	v_add_f32_e32 v74, 1.0, v74
	v_add_f32_e32 v102, 1.0, v102
	v_rcp_f32_e32 v74, v74
	s_waitcnt lgkmcnt(9)
	v_mfma_f32_16x16x32_bf16 v[128:131], v[246:249], v[128:131], 0
	v_rcp_f32_e32 v102, v102
	v_mul_f32_e32 v114, v74, v114
	v_mul_f32_e32 v115, v102, v115
	v_mfma_f32_16x16x32_bf16 v[84:87], v[190:193], v[174:177], v[84:87]
	v_lshlrev_b32_e32 v116, 16, v75
	v_and_b32_e32 v117, 0xffff0000, v75
	v_mul_f32_e32 v75, 0xbfb8aa3b, v116
	v_mfma_f32_16x16x32_bf16 v[92:95], v[202:205], v[174:177], v[92:95]
	v_mul_f32_e32 v102, 0xbfb8aa3b, v117
	v_exp_f32_e32 v75, v75
	v_exp_f32_e32 v102, v102
	v_mfma_f32_16x16x32_bf16 v[190:193], v[242:245], v[174:177], v[194:197]
	v_add_f32_e32 v75, 1.0, v75
	v_add_f32_e32 v102, 1.0, v102
	v_rcp_f32_e32 v75, v75
	s_waitcnt lgkmcnt(8)
	v_mfma_f32_16x16x32_bf16 v[128:131], v[250:253], v[174:177], v[128:131]
	v_rcp_f32_e32 v102, v102
	v_mul_f32_e32 v116, v75, v116
	v_mul_f32_e32 v117, v102, v117
	s_cmp_lg_u64 s[8:9], 0
	s_cbranch_scc0 .Lscan_zpf_skip
	v_lshl_add_u64 v[72:73], s[92:93], 0, v[122:123]
	s_mov_b64 s[10:11], 0x2001000
	v_lshl_add_u64 v[72:73], v[72:73], 0, s[6:7]
	v_lshl_add_u64 v[72:73], v[72:73], 0, s[10:11]
	global_load_dwordx4 v[76:79], v[72:73], off offset:128
	global_load_dwordx4 v[72:75], v[72:73], off offset:144
.Lscan_zpf_skip:
	ds_read_b128 v[174:177], v119 offset:55296
	ds_read_b128 v[194:197], v119 offset:55360
	ds_read_b128 v[202:205], v119 offset:57856
	ds_read_b128 v[234:237], v119 offset:57920
	ds_read_b128 v[238:241], v119 offset:60416
	ds_read_b128 v[242:245], v119 offset:60480
	ds_read_b128 v[246:249], v119 offset:62976
	ds_read_b128 v[250:253], v119 offset:63040
	v_cvt_pk_bf16_f32 v104, v84, v85
	v_cvt_pk_bf16_f32 v105, v86, v87
	v_cvt_pk_bf16_f32 v106, v92, v93
	v_cvt_pk_bf16_f32 v107, v94, v95
	v_cvt_pk_bf16_f32 v94, v128, v129
	v_cvt_pk_bf16_f32 v95, v130, v131
	s_waitcnt lgkmcnt(14)
	v_mfma_f32_16x16x32_bf16 v[84:87], v[182:185], v[104:107], v[88:91]
	v_cvt_pk_bf16_f32 v92, v190, v191
	v_cvt_pk_bf16_f32 v93, v192, v193
	v_pk_mul_f32 v[54:55], v[54:55], v[118:119] op_sel_hi:[1,0]
	s_waitcnt lgkmcnt(13)
	v_mfma_f32_16x16x32_bf16 v[88:91], v[210:213], v[104:107], v[178:181]
	v_mul_f32_e64 v52, v52, v118
	v_mul_f32_e64 v53, v53, v118
	v_pk_mul_f32 v[50:51], v[50:51], v[118:119] op_sel_hi:[1,0]
	v_pk_mul_f32 v[48:49], v[48:49], v[118:119] op_sel_hi:[1,0]
	s_waitcnt lgkmcnt(11)
	v_mfma_f32_16x16x32_bf16 v[128:131], v[218:221], v[104:107], v[186:189]
	v_mul_f32_e64 v46, v46, v118
	v_mul_f32_e64 v47, v47, v118
	v_pk_mul_f32 v[44:45], v[44:45], v[118:119] op_sel_hi:[1,0]
	v_pk_mul_f32 v[42:43], v[42:43], v[118:119] op_sel_hi:[1,0]
	v_mfma_f32_16x16x32_bf16 v[178:181], v[206:209], v[92:95], v[84:87]
	v_mul_f32_e64 v40, v40, v118
	v_mul_f32_e64 v41, v41, v118
	v_pk_mul_f32 v[62:63], v[62:63], v[118:119] op_sel_hi:[1,0]
	v_pk_mul_f32 v[60:61], v[60:61], v[118:119] op_sel_hi:[1,0]
	v_mfma_f32_16x16x32_bf16 v[88:91], v[214:217], v[92:95], v[88:91]
	v_mul_f32_e64 v58, v58, v118
	v_mul_f32_e64 v59, v59, v118
	v_pk_mul_f32 v[56:57], v[56:57], v[118:119] op_sel_hi:[1,0]
	v_pk_mul_f32 v[66:67], v[66:67], v[118:119] op_sel_hi:[1,0]
	s_waitcnt lgkmcnt(10)
	v_mfma_f32_16x16x32_bf16 v[84:87], v[222:225], v[92:95], v[128:131]
	s_nop 2
	ds_read_b128 v[128:131], v135
	ds_read_b128 v[182:185], v152
	ds_read_b128 v[186:189], v153
	ds_read_b128 v[190:193], v154
	ds_read_b128 v[206:209], v155
	ds_read_b128 v[210:213], v156
	ds_read_b128 v[214:217], v157
	ds_read_b128 v[218:221], v158
	v_pk_mul_f32 v[64:65], v[64:65], v[118:119] op_sel_hi:[1,0]
	v_pk_mul_f32 v[70:71], v[70:71], v[118:119] op_sel_hi:[1,0]
	s_waitcnt lgkmcnt(14)
	v_mfma_f32_16x16x32_bf16 v[80:83], v[226:229], v[104:107], v[80:83]
	v_mul_f32_e64 v68, v68, v118
	v_mul_f32_e64 v69, v69, v118
	v_mfma_f32_16x16x32_bf16 v[80:83], v[230:233], v[92:95], v[80:83]
	v_mfma_f32_16x16x32_bf16 v[52:55], v[174:177], v[104:107], v[52:55]
	v_mul_f32_e32 v226, v178, v178
	v_mul_f32_e32 v227, v179, v179
	v_mul_f32_e32 v228, v180, v180
	v_mul_f32_e32 v229, v181, v181
	v_mov_b32_dpp v222, v226 quad_perm:[1,0,3,2] row_mask:0xf bank_mask:0xf bound_ctrl:1
	v_mov_b32_dpp v223, v227 quad_perm:[1,0,3,2] row_mask:0xf bank_mask:0xf bound_ctrl:1
	v_mov_b32_dpp v224, v228 quad_perm:[1,0,3,2] row_mask:0xf bank_mask:0xf bound_ctrl:1
	v_mov_b32_dpp v225, v229 quad_perm:[1,0,3,2] row_mask:0xf bank_mask:0xf bound_ctrl:1
	s_waitcnt lgkmcnt(13)
	v_mfma_f32_16x16x32_bf16 v[48:51], v[202:205], v[104:107], v[48:51]
	v_fmac_f32_e32 v222, v178, v178
	v_fmac_f32_e32 v223, v179, v179
	v_fmac_f32_e32 v224, v180, v180
	v_fmac_f32_e32 v225, v181, v181
	v_mul_f32_e32 v178, v168, v178
	v_mul_f32_e32 v179, v168, v179
	v_mul_f32_e32 v180, v168, v180
	v_mul_f32_e32 v181, v168, v181
	s_waitcnt lgkmcnt(11)
	v_mfma_f32_16x16x32_bf16 v[44:47], v[238:241], v[104:107], v[44:47]
	v_cvt_pk_bf16_f32 v178, v178, s0
	v_cvt_pk_bf16_f32 v179, v179, s0
	v_cvt_pk_bf16_f32 v180, v180, s0
	v_cvt_pk_bf16_f32 v181, v181, s0
	v_add_f32_dpp v222, v222, v222 quad_perm:[2,3,0,1] row_mask:0xf bank_mask:0xf bound_ctrl:1
	v_add_f32_dpp v223, v223, v223 quad_perm:[2,3,0,1] row_mask:0xf bank_mask:0xf bound_ctrl:1
	v_add_f32_dpp v224, v224, v224 quad_perm:[2,3,0,1] row_mask:0xf bank_mask:0xf bound_ctrl:1
	v_add_f32_dpp v225, v225, v225 quad_perm:[2,3,0,1] row_mask:0xf bank_mask:0xf bound_ctrl:1
	s_waitcnt lgkmcnt(9)
	v_mfma_f32_16x16x32_bf16 v[40:43], v[246:249], v[104:107], v[40:43]
	v_add_f32_dpp v222, v222, v222 row_half_mirror row_mask:0xf bank_mask:0xf bound_ctrl:1
	v_add_f32_dpp v223, v223, v223 row_half_mirror row_mask:0xf bank_mask:0xf bound_ctrl:1
	v_add_f32_dpp v224, v224, v224 row_half_mirror row_mask:0xf bank_mask:0xf bound_ctrl:1
	v_add_f32_dpp v225, v225, v225 row_half_mirror row_mask:0xf bank_mask:0xf bound_ctrl:1
	v_add_f32_dpp v222, v222, v222 row_mirror row_mask:0xf bank_mask:0xf bound_ctrl:1
	v_add_f32_dpp v223, v223, v223 row_mirror row_mask:0xf bank_mask:0xf bound_ctrl:1
	v_add_f32_dpp v224, v224, v224 row_mirror row_mask:0xf bank_mask:0xf bound_ctrl:1
	v_add_f32_dpp v225, v225, v225 row_mirror row_mask:0xf bank_mask:0xf bound_ctrl:1
	v_mfma_f32_16x16x32_bf16 v[52:55], v[194:197], v[92:95], v[52:55]
	v_mul_f32_e32 v226, v88, v88
	v_mul_f32_e32 v227, v89, v89
	v_mul_f32_e32 v228, v90, v90
	v_mul_f32_e32 v229, v91, v91
	v_mov_b32_dpp v230, v226 quad_perm:[1,0,3,2] row_mask:0xf bank_mask:0xf bound_ctrl:1
	v_mov_b32_dpp v231, v227 quad_perm:[1,0,3,2] row_mask:0xf bank_mask:0xf bound_ctrl:1
	v_mov_b32_dpp v232, v228 quad_perm:[1,0,3,2] row_mask:0xf bank_mask:0xf bound_ctrl:1
	v_mov_b32_dpp v233, v229 quad_perm:[1,0,3,2] row_mask:0xf bank_mask:0xf bound_ctrl:1
	v_mfma_f32_16x16x32_bf16 v[48:51], v[234:237], v[92:95], v[48:51]
	v_fmac_f32_e32 v230, v88, v88
	v_fmac_f32_e32 v231, v89, v89
	v_fmac_f32_e32 v232, v90, v90
	v_fmac_f32_e32 v233, v91, v91
	v_mul_f32_e32 v88, v168, v88
	v_mul_f32_e32 v89, v168, v89
	v_mul_f32_e32 v90, v168, v90
	v_mul_f32_e32 v91, v168, v91
	v_mfma_f32_16x16x32_bf16 v[44:47], v[242:245], v[92:95], v[44:47]
	v_cvt_pk_bf16_f32 v88, v88, s0
	v_cvt_pk_bf16_f32 v89, v89, s0
	v_cvt_pk_bf16_f32 v90, v90, s0
	v_cvt_pk_bf16_f32 v91, v91, s0
	v_add_f32_dpp v230, v230, v230 quad_perm:[2,3,0,1] row_mask:0xf bank_mask:0xf bound_ctrl:1
	v_add_f32_dpp v231, v231, v231 quad_perm:[2,3,0,1] row_mask:0xf bank_mask:0xf bound_ctrl:1
	v_add_f32_dpp v232, v232, v232 quad_perm:[2,3,0,1] row_mask:0xf bank_mask:0xf bound_ctrl:1
	v_add_f32_dpp v233, v233, v233 quad_perm:[2,3,0,1] row_mask:0xf bank_mask:0xf bound_ctrl:1
	s_waitcnt lgkmcnt(8)
	v_mfma_f32_16x16x32_bf16 v[40:43], v[250:253], v[92:95], v[40:43]
	v_add_f32_dpp v230, v230, v230 row_half_mirror row_mask:0xf bank_mask:0xf bound_ctrl:1
	v_add_f32_dpp v231, v231, v231 row_half_mirror row_mask:0xf bank_mask:0xf bound_ctrl:1
	v_add_f32_dpp v232, v232, v232 row_half_mirror row_mask:0xf bank_mask:0xf bound_ctrl:1
	v_add_f32_dpp v233, v233, v233 row_half_mirror row_mask:0xf bank_mask:0xf bound_ctrl:1
	v_add_f32_dpp v230, v230, v230 row_mirror row_mask:0xf bank_mask:0xf bound_ctrl:1
	v_add_f32_dpp v231, v231, v231 row_mirror row_mask:0xf bank_mask:0xf bound_ctrl:1
	v_add_f32_dpp v232, v232, v232 row_mirror row_mask:0xf bank_mask:0xf bound_ctrl:1
	v_add_f32_dpp v233, v233, v233 row_mirror row_mask:0xf bank_mask:0xf bound_ctrl:1
	s_waitcnt lgkmcnt(7)
	v_mfma_f32_16x16x32_bf16 v[60:63], v[128:131], v[104:107], v[60:63]
	v_mul_f32_e32 v238, v84, v84
	v_mul_f32_e32 v239, v85, v85
	v_mul_f32_e32 v240, v86, v86
	v_mul_f32_e32 v241, v87, v87
	v_mov_b32_dpp v246, v238 quad_perm:[1,0,3,2] row_mask:0xf bank_mask:0xf bound_ctrl:1
	v_mov_b32_dpp v247, v239 quad_perm:[1,0,3,2] row_mask:0xf bank_mask:0xf bound_ctrl:1
	v_mov_b32_dpp v248, v240 quad_perm:[1,0,3,2] row_mask:0xf bank_mask:0xf bound_ctrl:1
	v_mov_b32_dpp v249, v241 quad_perm:[1,0,3,2] row_mask:0xf bank_mask:0xf bound_ctrl:1
	s_waitcnt lgkmcnt(5)
	v_mfma_f32_16x16x32_bf16 v[56:59], v[186:189], v[104:107], v[56:59]
	v_fmac_f32_e32 v246, v84, v84
	v_fmac_f32_e32 v247, v85, v85
	v_fmac_f32_e32 v248, v86, v86
	v_fmac_f32_e32 v249, v87, v87
	v_mul_f32_e32 v84, v168, v84
	v_mul_f32_e32 v85, v168, v85
	v_mul_f32_e32 v86, v168, v86
	v_mul_f32_e32 v87, v168, v87
	s_waitcnt lgkmcnt(3)
	v_mfma_f32_16x16x32_bf16 v[64:67], v[206:209], v[104:107], v[64:67]
	v_cvt_pk_bf16_f32 v84, v84, s0
	v_cvt_pk_bf16_f32 v85, v85, s0
	v_cvt_pk_bf16_f32 v86, v86, s0
	v_cvt_pk_bf16_f32 v87, v87, s0
	v_add_f32_dpp v246, v246, v246 quad_perm:[2,3,0,1] row_mask:0xf bank_mask:0xf bound_ctrl:1
	v_add_f32_dpp v247, v247, v247 quad_perm:[2,3,0,1] row_mask:0xf bank_mask:0xf bound_ctrl:1
	v_add_f32_dpp v248, v248, v248 quad_perm:[2,3,0,1] row_mask:0xf bank_mask:0xf bound_ctrl:1
	v_add_f32_dpp v249, v249, v249 quad_perm:[2,3,0,1] row_mask:0xf bank_mask:0xf bound_ctrl:1
	s_waitcnt lgkmcnt(1)
	v_mfma_f32_16x16x32_bf16 v[68:71], v[214:217], v[104:107], v[68:71]
	v_add_f32_dpp v246, v246, v246 row_half_mirror row_mask:0xf bank_mask:0xf bound_ctrl:1
	v_add_f32_dpp v247, v247, v247 row_half_mirror row_mask:0xf bank_mask:0xf bound_ctrl:1
	v_add_f32_dpp v248, v248, v248 row_half_mirror row_mask:0xf bank_mask:0xf bound_ctrl:1
	v_add_f32_dpp v249, v249, v249 row_half_mirror row_mask:0xf bank_mask:0xf bound_ctrl:1
	v_add_f32_dpp v246, v246, v246 row_mirror row_mask:0xf bank_mask:0xf bound_ctrl:1
	v_add_f32_dpp v247, v247, v247 row_mirror row_mask:0xf bank_mask:0xf bound_ctrl:1
	v_add_f32_dpp v248, v248, v248 row_mirror row_mask:0xf bank_mask:0xf bound_ctrl:1
	v_add_f32_dpp v249, v249, v249 row_mirror row_mask:0xf bank_mask:0xf bound_ctrl:1
	v_mfma_f32_16x16x32_bf16 v[60:63], v[182:185], v[92:95], v[60:63]
	v_mul_f32_e32 v238, v80, v80
	v_mul_f32_e32 v239, v81, v81
	v_mul_f32_e32 v240, v82, v82
	v_mul_f32_e32 v241, v83, v83
	v_mov_b32_dpp v250, v238 quad_perm:[1,0,3,2] row_mask:0xf bank_mask:0xf bound_ctrl:1
	v_mov_b32_dpp v251, v239 quad_perm:[1,0,3,2] row_mask:0xf bank_mask:0xf bound_ctrl:1
	v_mov_b32_dpp v252, v240 quad_perm:[1,0,3,2] row_mask:0xf bank_mask:0xf bound_ctrl:1
	v_mov_b32_dpp v253, v241 quad_perm:[1,0,3,2] row_mask:0xf bank_mask:0xf bound_ctrl:1
	v_mfma_f32_16x16x32_bf16 v[56:59], v[190:193], v[92:95], v[56:59]
	v_fmac_f32_e32 v250, v80, v80
	v_fmac_f32_e32 v251, v81, v81
	v_fmac_f32_e32 v252, v82, v82
	v_fmac_f32_e32 v253, v83, v83
	v_mul_f32_e32 v80, v168, v80
	v_mul_f32_e32 v81, v168, v81
	v_mul_f32_e32 v82, v168, v82
	v_mul_f32_e32 v83, v168, v83
	v_mfma_f32_16x16x32_bf16 v[64:67], v[210:213], v[92:95], v[64:67]
	v_cvt_pk_bf16_f32 v80, v80, s0
	v_cvt_pk_bf16_f32 v81, v81, s0
	v_cvt_pk_bf16_f32 v82, v82, s0
	v_cvt_pk_bf16_f32 v83, v83, s0
	v_add_f32_dpp v250, v250, v250 quad_perm:[2,3,0,1] row_mask:0xf bank_mask:0xf bound_ctrl:1
	v_add_f32_dpp v251, v251, v251 quad_perm:[2,3,0,1] row_mask:0xf bank_mask:0xf bound_ctrl:1
	v_add_f32_dpp v252, v252, v252 quad_perm:[2,3,0,1] row_mask:0xf bank_mask:0xf bound_ctrl:1
	v_add_f32_dpp v253, v253, v253 quad_perm:[2,3,0,1] row_mask:0xf bank_mask:0xf bound_ctrl:1
	s_waitcnt lgkmcnt(0)
	v_mfma_f32_16x16x32_bf16 v[68:71], v[218:221], v[92:95], v[68:71]
	v_add_f32_dpp v250, v250, v250 row_half_mirror row_mask:0xf bank_mask:0xf bound_ctrl:1
	v_add_f32_dpp v251, v251, v251 row_half_mirror row_mask:0xf bank_mask:0xf bound_ctrl:1
	v_add_f32_dpp v252, v252, v252 row_half_mirror row_mask:0xf bank_mask:0xf bound_ctrl:1
	v_add_f32_dpp v253, v253, v253 row_half_mirror row_mask:0xf bank_mask:0xf bound_ctrl:1
	v_add_f32_dpp v250, v250, v250 row_mirror row_mask:0xf bank_mask:0xf bound_ctrl:1
	v_add_f32_dpp v251, v251, v251 row_mirror row_mask:0xf bank_mask:0xf bound_ctrl:1
	v_add_f32_dpp v252, v252, v252 row_mirror row_mask:0xf bank_mask:0xf bound_ctrl:1
	v_add_f32_dpp v253, v253, v253 row_mirror row_mask:0xf bank_mask:0xf bound_ctrl:1
	ds_write_b16 v171, v178
	ds_write_b16 v171, v179 offset:288
	ds_write_b16 v171, v180 offset:576
	ds_write_b16 v171, v181 offset:864
	ds_write_b16 v171, v88 offset:4608
	ds_write_b16 v171, v89 offset:4896
	ds_write_b16 v171, v90 offset:5184
	ds_write_b16 v171, v91 offset:5472
	ds_write_b16 v171, v84 offset:9216
	ds_write_b16 v171, v85 offset:9504
	ds_write_b16 v171, v86 offset:9792
	ds_write_b16 v171, v87 offset:10080
	ds_write_b16 v171, v80 offset:13824
	ds_write_b16 v171, v81 offset:14112
	ds_write_b16 v171, v82 offset:14400
	ds_write_b16 v171, v83 offset:14688
	s_and_saveexec_b64 s[10:11], s[4:5]
	ds_write_b128 v169, v[222:225]
	ds_write_b128 v169, v[230:233] offset:64
	ds_write_b128 v169, v[246:249] offset:128
	ds_write_b128 v169, v[250:253] offset:192
	s_or_b64 exec, exec, s[10:11]
	s_andn2_b64 vcc, exec, s[8:9]
	s_waitcnt lgkmcnt(0)
	s_barrier
	ds_read2st64_b32 v[174:175], v137 offset1:1
	ds_read2st64_b32 v[176:177], v137 offset0:2 offset1:3
	ds_read2st64_b32 v[178:179], v137 offset0:4 offset1:5
	ds_read2st64_b32 v[180:181], v137 offset0:6 offset1:7
	ds_read_b128 v[84:87], v163
	ds_read_b128 v[80:83], v163 offset:16
	s_cbranch_vccnz .Lscan_last
	s_waitcnt vmcnt(2)
	v_mov_b32_e32 v118, v172
	ds_write_b128 v164, v[0:3]
	ds_write_b128 v164, v[4:7] offset:16
	ds_write_b128 v164, v[8:11] offset:18432
	ds_write_b128 v164, v[12:15] offset:18448
	ds_write_b128 v164, v[16:19] offset:36864
	ds_write_b128 v164, v[20:23] offset:36880
	ds_write_b128 v165, v[32:35] offset:55296
	ds_write_b128 v165, v[36:39] offset:55312
	ds_write_b128 v166, v[24:27]
	ds_write_b128 v167, v[28:31]
	s_branch .LBB0_708

.LBB0_752:
	v_readlane_b32 s28, v255, 46
	v_readlane_b32 s29, v255, 47
	v_readlane_b32 s30, v255, 54
	v_mov_b32_e32 v70, 0
	s_lshl_b32 s0, s58, 7
	s_and_b32 s4, s0, 0x180
	v_readlane_b32 s16, v254, 16
	v_readlane_b32 s17, v254, 17
	v_or_b32_e32 v75, s4, v136
	v_lshlrev_b32_e32 v75, 2, v75
	s_nop 4
	global_load_dword v74, v75, s[16:17]
	global_load_dword v73, v75, s[16:17] offset:128
	global_load_dword v72, v75, s[16:17] offset:256
	global_load_dword v71, v75, s[16:17] offset:384
	s_and_saveexec_b64 s[0:1], s[88:89]
	s_cbranch_execnz .LBB0_886

.LBB0_755:
	s_or_b64 exec, exec, s[0:1]
	s_lshl_b32 s0, s58, 7
	s_and_b32 s4, s0, 0x180
	v_readlane_b32 s12, v254, 12
	s_waitcnt lgkmcnt(0)
	ds_read_b128 v[80:83], v217
	ds_read_b128 v[84:87], v217 offset:32
	ds_read_b128 v[88:91], v217 offset:64
	ds_read_b128 v[92:95], v217 offset:96
	v_readlane_b32 s16, v254, 16
	v_readlane_b32 s17, v254, 17
	v_and_b32_e32 v67, 64, v201
	v_xor_b32_e32 v66, 16, v201
	v_add_u32_e32 v67, 64, v67
	v_cmp_lt_i32_e32 vcc, v66, v67
	s_lshl_b32 s0, s58, 9
	s_and_b32 s0, s0, 0x7800
	s_add_u32 s0, s59, s0
	s_addc_u32 s1, s76, 0
	v_cndmask_b32_e32 v66, v201, v66, vcc
	s_lshl_b64 s[0:1], s[0:1], 11
	v_readlane_b32 s10, v254, 44
	v_readlane_b32 s11, v254, 45
	v_lshlrev_b32_e32 v75, 2, v66
	v_mov_b32_e32 v76, 0x3020706
	v_mov_b32_e32 v77, 0x5040100
	s_add_u32 s0, s10, s0
	s_addc_u32 s1, s11, s1
	s_lshl_b32 s4, s4, 1
	s_add_u32 s0, s0, s4
	s_addc_u32 s1, s1, 0
	v_cndmask_b32_e64 v76, v76, v77, s[8:9]
	v_and_b32_e32 v0, 30, v136
	v_and_b32_e32 v77, 1, v136
	v_lshlrev_b32_e32 v0, 1, v0
	v_lshl_or_b32 v0, v77, 11, v0
	v_readlane_b32 s13, v254, 13
	v_lshl_add_u64 v[66:67], s[0:1], 0, v[0:1]
	v_readlane_b32 s14, v254, 14
	v_readlane_b32 s15, v254, 15
	v_readlane_b32 s18, v254, 18
	v_readlane_b32 s19, v254, 19
	v_readlane_b32 s20, v254, 20
	v_readlane_b32 s21, v254, 21
	v_readlane_b32 s22, v254, 22
	v_readlane_b32 s23, v254, 23
	v_readlane_b32 s24, v254, 24
	v_readlane_b32 s25, v254, 25
	v_readlane_b32 s26, v254, 26
	v_readlane_b32 s27, v254, 27
	s_waitcnt lgkmcnt(0)
	v_rcp_f32_e32 v80, v80
	v_rcp_f32_e32 v81, v81
	v_rcp_f32_e32 v82, v82
	v_rcp_f32_e32 v83, v83
	v_rcp_f32_e32 v84, v84
	v_rcp_f32_e32 v85, v85
	v_rcp_f32_e32 v86, v86
	v_rcp_f32_e32 v87, v87
	v_rcp_f32_e32 v88, v88
	v_rcp_f32_e32 v89, v89
	v_rcp_f32_e32 v90, v90
	v_rcp_f32_e32 v91, v91
	v_rcp_f32_e32 v92, v92
	v_rcp_f32_e32 v93, v93
	v_rcp_f32_e32 v94, v94
	v_rcp_f32_e32 v95, v95
	v_mul_f32_e32 v34, v34, v80
	v_mul_f32_e32 v35, v35, v81
	v_mul_f32_e32 v50, v50, v80
	v_mul_f32_e32 v51, v51, v81
	v_mul_f32_e32 v18, v18, v80
	v_mul_f32_e32 v19, v19, v81
	v_mul_f32_e32 v2, v2, v80
	v_mul_f32_e32 v3, v3, v81
	v_mul_f32_e32 v80, v34, v34
	v_mul_f32_e32 v81, v35, v35
	v_fmac_f32_e32 v80, v50, v50
	v_fmac_f32_e32 v81, v51, v51
	v_fmac_f32_e32 v80, v18, v18
	v_fmac_f32_e32 v81, v19, v19
	v_fmac_f32_e32 v80, v2, v2
	v_fmac_f32_e32 v81, v3, v3
	v_mul_f32_e32 v36, v36, v82
	v_mul_f32_e32 v37, v37, v83
	v_mul_f32_e32 v52, v52, v82
	v_mul_f32_e32 v53, v53, v83
	v_mul_f32_e32 v20, v20, v82
	v_mul_f32_e32 v21, v21, v83
	v_mul_f32_e32 v4, v4, v82
	v_mul_f32_e32 v5, v5, v83
	v_mul_f32_e32 v82, v36, v36
	v_mul_f32_e32 v83, v37, v37
	v_fmac_f32_e32 v82, v52, v52
	v_fmac_f32_e32 v83, v53, v53
	v_fmac_f32_e32 v82, v20, v20
	v_fmac_f32_e32 v83, v21, v21
	v_fmac_f32_e32 v82, v4, v4
	v_fmac_f32_e32 v83, v5, v5
	v_mul_f32_e32 v38, v38, v84
	v_mul_f32_e32 v39, v39, v85
	v_mul_f32_e32 v54, v54, v84
	v_mul_f32_e32 v55, v55, v85
	v_mul_f32_e32 v22, v22, v84
	v_mul_f32_e32 v23, v23, v85
	v_mul_f32_e32 v6, v6, v84
	v_mul_f32_e32 v7, v7, v85
	v_mul_f32_e32 v84, v38, v38
	v_mul_f32_e32 v85, v39, v39
	v_fmac_f32_e32 v84, v54, v54
	v_fmac_f32_e32 v85, v55, v55
	v_fmac_f32_e32 v84, v22, v22
	v_fmac_f32_e32 v85, v23, v23
	v_fmac_f32_e32 v84, v6, v6
	v_fmac_f32_e32 v85, v7, v7
	v_mul_f32_e32 v40, v40, v86
	v_mul_f32_e32 v41, v41, v87
	v_mul_f32_e32 v56, v56, v86
	v_mul_f32_e32 v57, v57, v87
	v_mul_f32_e32 v24, v24, v86
	v_mul_f32_e32 v25, v25, v87
	v_mul_f32_e32 v8, v8, v86
	v_mul_f32_e32 v9, v9, v87
	v_mul_f32_e32 v86, v40, v40
	v_mul_f32_e32 v87, v41, v41
	v_fmac_f32_e32 v86, v56, v56
	v_fmac_f32_e32 v87, v57, v57
	v_fmac_f32_e32 v86, v24, v24
	v_fmac_f32_e32 v87, v25, v25
	v_fmac_f32_e32 v86, v8, v8
	v_fmac_f32_e32 v87, v9, v9
	v_mul_f32_e32 v42, v42, v88
	v_mul_f32_e32 v43, v43, v89
	v_mul_f32_e32 v58, v58, v88
	v_mul_f32_e32 v59, v59, v89
	v_mul_f32_e32 v26, v26, v88
	v_mul_f32_e32 v27, v27, v89
	v_mul_f32_e32 v10, v10, v88
	v_mul_f32_e32 v11, v11, v89
	v_mul_f32_e32 v88, v42, v42
	v_mul_f32_e32 v89, v43, v43
	v_fmac_f32_e32 v88, v58, v58
	v_fmac_f32_e32 v89, v59, v59
	v_fmac_f32_e32 v88, v26, v26
	v_fmac_f32_e32 v89, v27, v27
	v_fmac_f32_e32 v88, v10, v10
	v_fmac_f32_e32 v89, v11, v11
	v_mul_f32_e32 v44, v44, v90
	v_mul_f32_e32 v45, v45, v91
	v_mul_f32_e32 v60, v60, v90
	v_mul_f32_e32 v61, v61, v91
	v_mul_f32_e32 v28, v28, v90
	v_mul_f32_e32 v29, v29, v91
	v_mul_f32_e32 v12, v12, v90
	v_mul_f32_e32 v13, v13, v91
	v_mul_f32_e32 v90, v44, v44
	v_mul_f32_e32 v91, v45, v45
	v_fmac_f32_e32 v90, v60, v60
	v_fmac_f32_e32 v91, v61, v61
	v_fmac_f32_e32 v90, v28, v28
	v_fmac_f32_e32 v91, v29, v29
	v_fmac_f32_e32 v90, v12, v12
	v_fmac_f32_e32 v91, v13, v13
	v_mul_f32_e32 v46, v46, v92
	v_mul_f32_e32 v47, v47, v93
	v_mul_f32_e32 v62, v62, v92
	v_mul_f32_e32 v63, v63, v93
	v_mul_f32_e32 v30, v30, v92
	v_mul_f32_e32 v31, v31, v93
	v_mul_f32_e32 v14, v14, v92
	v_mul_f32_e32 v15, v15, v93
	v_mul_f32_e32 v92, v46, v46
	v_mul_f32_e32 v93, v47, v47
	v_fmac_f32_e32 v92, v62, v62
	v_fmac_f32_e32 v93, v63, v63
	v_fmac_f32_e32 v92, v30, v30
	v_fmac_f32_e32 v93, v31, v31
	v_fmac_f32_e32 v92, v14, v14
	v_fmac_f32_e32 v93, v15, v15
	v_mul_f32_e32 v48, v48, v94
	v_mul_f32_e32 v49, v49, v95
	v_mul_f32_e32 v64, v64, v94
	v_mul_f32_e32 v65, v65, v95
	v_mul_f32_e32 v32, v32, v94
	v_mul_f32_e32 v33, v33, v95
	v_mul_f32_e32 v16, v16, v94
	v_mul_f32_e32 v17, v17, v95
	v_mul_f32_e32 v94, v48, v48
	v_mul_f32_e32 v95, v49, v49
	v_fmac_f32_e32 v94, v64, v64
	v_fmac_f32_e32 v95, v65, v65
	v_fmac_f32_e32 v94, v32, v32
	v_fmac_f32_e32 v95, v33, v33
	v_fmac_f32_e32 v94, v16, v16
	v_fmac_f32_e32 v95, v17, v17
	v_add_f32_dpp v80, v80, v80 quad_perm:[1,0,3,2] row_mask:0xf bank_mask:0xf bound_ctrl:1
	v_add_f32_dpp v81, v81, v81 quad_perm:[1,0,3,2] row_mask:0xf bank_mask:0xf bound_ctrl:1
	v_add_f32_dpp v82, v82, v82 quad_perm:[1,0,3,2] row_mask:0xf bank_mask:0xf bound_ctrl:1
	v_add_f32_dpp v83, v83, v83 quad_perm:[1,0,3,2] row_mask:0xf bank_mask:0xf bound_ctrl:1
	v_add_f32_dpp v84, v84, v84 quad_perm:[1,0,3,2] row_mask:0xf bank_mask:0xf bound_ctrl:1
	v_add_f32_dpp v85, v85, v85 quad_perm:[1,0,3,2] row_mask:0xf bank_mask:0xf bound_ctrl:1
	v_add_f32_dpp v86, v86, v86 quad_perm:[1,0,3,2] row_mask:0xf bank_mask:0xf bound_ctrl:1
	v_add_f32_dpp v87, v87, v87 quad_perm:[1,0,3,2] row_mask:0xf bank_mask:0xf bound_ctrl:1
	v_add_f32_dpp v88, v88, v88 quad_perm:[1,0,3,2] row_mask:0xf bank_mask:0xf bound_ctrl:1
	v_add_f32_dpp v89, v89, v89 quad_perm:[1,0,3,2] row_mask:0xf bank_mask:0xf bound_ctrl:1
	v_add_f32_dpp v90, v90, v90 quad_perm:[1,0,3,2] row_mask:0xf bank_mask:0xf bound_ctrl:1
	v_add_f32_dpp v91, v91, v91 quad_perm:[1,0,3,2] row_mask:0xf bank_mask:0xf bound_ctrl:1
	v_add_f32_dpp v92, v92, v92 quad_perm:[1,0,3,2] row_mask:0xf bank_mask:0xf bound_ctrl:1
	v_add_f32_dpp v93, v93, v93 quad_perm:[1,0,3,2] row_mask:0xf bank_mask:0xf bound_ctrl:1
	v_add_f32_dpp v94, v94, v94 quad_perm:[1,0,3,2] row_mask:0xf bank_mask:0xf bound_ctrl:1
	v_add_f32_dpp v95, v95, v95 quad_perm:[1,0,3,2] row_mask:0xf bank_mask:0xf bound_ctrl:1
	v_add_f32_dpp v80, v80, v80 quad_perm:[2,3,0,1] row_mask:0xf bank_mask:0xf bound_ctrl:1
	v_add_f32_dpp v81, v81, v81 quad_perm:[2,3,0,1] row_mask:0xf bank_mask:0xf bound_ctrl:1
	v_add_f32_dpp v82, v82, v82 quad_perm:[2,3,0,1] row_mask:0xf bank_mask:0xf bound_ctrl:1
	v_add_f32_dpp v83, v83, v83 quad_perm:[2,3,0,1] row_mask:0xf bank_mask:0xf bound_ctrl:1
	v_add_f32_dpp v84, v84, v84 quad_perm:[2,3,0,1] row_mask:0xf bank_mask:0xf bound_ctrl:1
	v_add_f32_dpp v85, v85, v85 quad_perm:[2,3,0,1] row_mask:0xf bank_mask:0xf bound_ctrl:1
	v_add_f32_dpp v86, v86, v86 quad_perm:[2,3,0,1] row_mask:0xf bank_mask:0xf bound_ctrl:1
	v_add_f32_dpp v87, v87, v87 quad_perm:[2,3,0,1] row_mask:0xf bank_mask:0xf bound_ctrl:1
	v_add_f32_dpp v88, v88, v88 quad_perm:[2,3,0,1] row_mask:0xf bank_mask:0xf bound_ctrl:1
	v_add_f32_dpp v89, v89, v89 quad_perm:[2,3,0,1] row_mask:0xf bank_mask:0xf bound_ctrl:1
	v_add_f32_dpp v90, v90, v90 quad_perm:[2,3,0,1] row_mask:0xf bank_mask:0xf bound_ctrl:1
	v_add_f32_dpp v91, v91, v91 quad_perm:[2,3,0,1] row_mask:0xf bank_mask:0xf bound_ctrl:1
	v_add_f32_dpp v92, v92, v92 quad_perm:[2,3,0,1] row_mask:0xf bank_mask:0xf bound_ctrl:1
	v_add_f32_dpp v93, v93, v93 quad_perm:[2,3,0,1] row_mask:0xf bank_mask:0xf bound_ctrl:1
	v_add_f32_dpp v94, v94, v94 quad_perm:[2,3,0,1] row_mask:0xf bank_mask:0xf bound_ctrl:1
	v_add_f32_dpp v95, v95, v95 quad_perm:[2,3,0,1] row_mask:0xf bank_mask:0xf bound_ctrl:1
	v_add_f32_dpp v80, v80, v80 row_half_mirror row_mask:0xf bank_mask:0xf bound_ctrl:1
	v_add_f32_dpp v81, v81, v81 row_half_mirror row_mask:0xf bank_mask:0xf bound_ctrl:1
	v_add_f32_dpp v82, v82, v82 row_half_mirror row_mask:0xf bank_mask:0xf bound_ctrl:1
	v_add_f32_dpp v83, v83, v83 row_half_mirror row_mask:0xf bank_mask:0xf bound_ctrl:1
	v_add_f32_dpp v84, v84, v84 row_half_mirror row_mask:0xf bank_mask:0xf bound_ctrl:1
	v_add_f32_dpp v85, v85, v85 row_half_mirror row_mask:0xf bank_mask:0xf bound_ctrl:1
	v_add_f32_dpp v86, v86, v86 row_half_mirror row_mask:0xf bank_mask:0xf bound_ctrl:1
	v_add_f32_dpp v87, v87, v87 row_half_mirror row_mask:0xf bank_mask:0xf bound_ctrl:1
	v_add_f32_dpp v88, v88, v88 row_half_mirror row_mask:0xf bank_mask:0xf bound_ctrl:1
	v_add_f32_dpp v89, v89, v89 row_half_mirror row_mask:0xf bank_mask:0xf bound_ctrl:1
	v_add_f32_dpp v90, v90, v90 row_half_mirror row_mask:0xf bank_mask:0xf bound_ctrl:1
	v_add_f32_dpp v91, v91, v91 row_half_mirror row_mask:0xf bank_mask:0xf bound_ctrl:1
	v_add_f32_dpp v92, v92, v92 row_half_mirror row_mask:0xf bank_mask:0xf bound_ctrl:1
	v_add_f32_dpp v93, v93, v93 row_half_mirror row_mask:0xf bank_mask:0xf bound_ctrl:1
	v_add_f32_dpp v94, v94, v94 row_half_mirror row_mask:0xf bank_mask:0xf bound_ctrl:1
	v_add_f32_dpp v95, v95, v95 row_half_mirror row_mask:0xf bank_mask:0xf bound_ctrl:1
	v_add_f32_dpp v80, v80, v80 row_mirror row_mask:0xf bank_mask:0xf bound_ctrl:1
	v_add_f32_dpp v81, v81, v81 row_mirror row_mask:0xf bank_mask:0xf bound_ctrl:1
	v_add_f32_dpp v82, v82, v82 row_mirror row_mask:0xf bank_mask:0xf bound_ctrl:1
	v_add_f32_dpp v83, v83, v83 row_mirror row_mask:0xf bank_mask:0xf bound_ctrl:1
	v_add_f32_dpp v84, v84, v84 row_mirror row_mask:0xf bank_mask:0xf bound_ctrl:1
	v_add_f32_dpp v85, v85, v85 row_mirror row_mask:0xf bank_mask:0xf bound_ctrl:1
	v_add_f32_dpp v86, v86, v86 row_mirror row_mask:0xf bank_mask:0xf bound_ctrl:1
	v_add_f32_dpp v87, v87, v87 row_mirror row_mask:0xf bank_mask:0xf bound_ctrl:1
	v_add_f32_dpp v88, v88, v88 row_mirror row_mask:0xf bank_mask:0xf bound_ctrl:1
	v_add_f32_dpp v89, v89, v89 row_mirror row_mask:0xf bank_mask:0xf bound_ctrl:1
	v_add_f32_dpp v90, v90, v90 row_mirror row_mask:0xf bank_mask:0xf bound_ctrl:1
	v_add_f32_dpp v91, v91, v91 row_mirror row_mask:0xf bank_mask:0xf bound_ctrl:1
	v_add_f32_dpp v92, v92, v92 row_mirror row_mask:0xf bank_mask:0xf bound_ctrl:1
	v_add_f32_dpp v93, v93, v93 row_mirror row_mask:0xf bank_mask:0xf bound_ctrl:1
	v_add_f32_dpp v94, v94, v94 row_mirror row_mask:0xf bank_mask:0xf bound_ctrl:1
	v_add_f32_dpp v95, v95, v95 row_mirror row_mask:0xf bank_mask:0xf bound_ctrl:1
	ds_bpermute_b32 v98, v75, v80
	ds_bpermute_b32 v99, v75, v81
	ds_bpermute_b32 v100, v75, v82
	ds_bpermute_b32 v101, v75, v83
	ds_bpermute_b32 v102, v75, v84
	ds_bpermute_b32 v103, v75, v85
	ds_bpermute_b32 v104, v75, v86
	ds_bpermute_b32 v105, v75, v87
	ds_bpermute_b32 v106, v75, v88
	ds_bpermute_b32 v107, v75, v89
	ds_bpermute_b32 v108, v75, v90
	ds_bpermute_b32 v109, v75, v91
	ds_bpermute_b32 v110, v75, v92
	ds_bpermute_b32 v111, v75, v93
	ds_bpermute_b32 v112, v75, v94
	ds_bpermute_b32 v113, v75, v95
	s_cmp_lg_u64 s[88:89], 0
	s_cbranch_scc1 .Lattn_w0
	s_waitcnt vmcnt(0)
	s_branch .Lattn_wj

.Lattn_wj:
	s_waitcnt lgkmcnt(15)
	v_add_f32_e32 v80, v80, v98
	s_waitcnt lgkmcnt(14)
	v_add_f32_e32 v81, v81, v99
	s_waitcnt lgkmcnt(13)
	v_add_f32_e32 v82, v82, v100
	s_waitcnt lgkmcnt(12)
	v_add_f32_e32 v83, v83, v101
	s_waitcnt lgkmcnt(11)
	v_add_f32_e32 v84, v84, v102
	s_waitcnt lgkmcnt(10)
	v_add_f32_e32 v85, v85, v103
	s_waitcnt lgkmcnt(9)
	v_add_f32_e32 v86, v86, v104
	s_waitcnt lgkmcnt(8)
	v_add_f32_e32 v87, v87, v105
	s_waitcnt lgkmcnt(7)
	v_add_f32_e32 v88, v88, v106
	s_waitcnt lgkmcnt(6)
	v_add_f32_e32 v89, v89, v107
	s_waitcnt lgkmcnt(5)
	v_add_f32_e32 v90, v90, v108
	s_waitcnt lgkmcnt(4)
	v_add_f32_e32 v91, v91, v109
	s_waitcnt lgkmcnt(3)
	v_add_f32_e32 v92, v92, v110
	s_waitcnt lgkmcnt(2)
	v_add_f32_e32 v93, v93, v111
	s_waitcnt lgkmcnt(1)
	v_add_f32_e32 v94, v94, v112
	s_waitcnt lgkmcnt(0)
	v_add_f32_e32 v95, v95, v113
	v_fmamk_f32 v80, v80, 0x3c000000, v210
	v_fmamk_f32 v81, v81, 0x3c000000, v210
	v_fmamk_f32 v82, v82, 0x3c000000, v210
	v_fmamk_f32 v83, v83, 0x3c000000, v210
	v_fmamk_f32 v84, v84, 0x3c000000, v210
	v_fmamk_f32 v85, v85, 0x3c000000, v210
	v_fmamk_f32 v86, v86, 0x3c000000, v210
	v_fmamk_f32 v87, v87, 0x3c000000, v210
	v_fmamk_f32 v88, v88, 0x3c000000, v210
	v_fmamk_f32 v89, v89, 0x3c000000, v210
	v_fmamk_f32 v90, v90, 0x3c000000, v210
	v_fmamk_f32 v91, v91, 0x3c000000, v210
	v_fmamk_f32 v92, v92, 0x3c000000, v210
	v_fmamk_f32 v93, v93, 0x3c000000, v210
	v_fmamk_f32 v94, v94, 0x3c000000, v210
	v_fmamk_f32 v95, v95, 0x3c000000, v210
	v_rsq_f32_e32 v80, v80
	v_rsq_f32_e32 v81, v81
	v_rsq_f32_e32 v82, v82
	v_rsq_f32_e32 v83, v83
	v_rsq_f32_e32 v84, v84
	v_rsq_f32_e32 v85, v85
	v_rsq_f32_e32 v86, v86
	v_rsq_f32_e32 v87, v87
	v_rsq_f32_e32 v88, v88
	v_rsq_f32_e32 v89, v89
	v_rsq_f32_e32 v90, v90
	v_rsq_f32_e32 v91, v91
	v_rsq_f32_e32 v92, v92
	v_rsq_f32_e32 v93, v93
	v_rsq_f32_e32 v94, v94
	v_rsq_f32_e32 v95, v95
	v_mul_f32_e32 v50, v50, v80
	v_mul_f32_e32 v51, v51, v81
	v_mul_f32_e32 v34, v34, v80
	v_mul_f32_e32 v35, v35, v81
	v_mul_f32_e32 v18, v18, v80
	v_mul_f32_e32 v19, v19, v81
	v_mul_f32_e32 v2, v2, v80
	v_mul_f32_e32 v3, v3, v81
	v_mul_f32_e32 v50, v74, v50
	v_mul_f32_e32 v51, v74, v51
	v_mul_f32_e32 v34, v73, v34
	v_mul_f32_e32 v35, v73, v35
	v_mul_f32_e32 v18, v72, v18
	v_mul_f32_e32 v19, v72, v19
	v_mul_f32_e32 v2, v71, v2
	v_mul_f32_e32 v3, v71, v3
	v_lshl_add_u64 v[68:69], v[66:67], 0, v[152:153]
	v_cvt_pk_bf16_f32 v114, v50, v51
	v_cvt_pk_bf16_f32 v116, v34, v35
	v_cvt_pk_bf16_f32 v118, v18, v19
	v_cvt_pk_bf16_f32 v120, v2, v3
	v_mov_b32_dpp v115, v114 quad_perm:[1,0,3,2] row_mask:0xf bank_mask:0xf bound_ctrl:1
	v_mov_b32_dpp v117, v116 quad_perm:[1,0,3,2] row_mask:0xf bank_mask:0xf bound_ctrl:1
	v_mov_b32_dpp v119, v118 quad_perm:[1,0,3,2] row_mask:0xf bank_mask:0xf bound_ctrl:1
	v_mov_b32_dpp v121, v120 quad_perm:[1,0,3,2] row_mask:0xf bank_mask:0xf bound_ctrl:1
	v_perm_b32 v115, v115, v114, v76
	global_store_dword v[68:69], v115, off
	v_perm_b32 v117, v117, v116, v76
	global_store_dword v[68:69], v117, off offset:64
	v_perm_b32 v119, v119, v118, v76
	global_store_dword v[68:69], v119, off offset:128
	v_perm_b32 v121, v121, v120, v76
	global_store_dword v[68:69], v121, off offset:192
	v_mul_f32_e32 v52, v52, v82
	v_mul_f32_e32 v53, v53, v83
	v_mul_f32_e32 v36, v36, v82
	v_mul_f32_e32 v37, v37, v83
	v_mul_f32_e32 v20, v20, v82
	v_mul_f32_e32 v21, v21, v83
	v_mul_f32_e32 v4, v4, v82
	v_mul_f32_e32 v5, v5, v83
	v_mul_f32_e32 v52, v74, v52
	v_mul_f32_e32 v53, v74, v53
	v_mul_f32_e32 v36, v73, v36
	v_mul_f32_e32 v37, v73, v37
	v_mul_f32_e32 v20, v72, v20
	v_mul_f32_e32 v21, v72, v21
	v_mul_f32_e32 v4, v71, v4
	v_mul_f32_e32 v5, v71, v5
	v_lshl_add_u64 v[68:69], v[66:67], 0, v[156:157]
	v_cvt_pk_bf16_f32 v122, v52, v53
	v_cvt_pk_bf16_f32 v124, v36, v37
	v_cvt_pk_bf16_f32 v126, v20, v21
	v_cvt_pk_bf16_f32 v128, v4, v5
	v_mov_b32_dpp v123, v122 quad_perm:[1,0,3,2] row_mask:0xf bank_mask:0xf bound_ctrl:1
	v_mov_b32_dpp v125, v124 quad_perm:[1,0,3,2] row_mask:0xf bank_mask:0xf bound_ctrl:1
	v_mov_b32_dpp v127, v126 quad_perm:[1,0,3,2] row_mask:0xf bank_mask:0xf bound_ctrl:1
	v_mov_b32_dpp v129, v128 quad_perm:[1,0,3,2] row_mask:0xf bank_mask:0xf bound_ctrl:1
	v_perm_b32 v123, v123, v122, v76
	global_store_dword v[68:69], v123, off
	v_perm_b32 v125, v125, v124, v76
	global_store_dword v[68:69], v125, off offset:64
	v_perm_b32 v127, v127, v126, v76
	global_store_dword v[68:69], v127, off offset:128
	v_perm_b32 v129, v129, v128, v76
	global_store_dword v[68:69], v129, off offset:192
	v_mul_f32_e32 v54, v54, v84
	v_mul_f32_e32 v55, v55, v85
	v_mul_f32_e32 v38, v38, v84
	v_mul_f32_e32 v39, v39, v85
	v_mul_f32_e32 v22, v22, v84
	v_mul_f32_e32 v23, v23, v85
	v_mul_f32_e32 v6, v6, v84
	v_mul_f32_e32 v7, v7, v85
	v_mul_f32_e32 v54, v74, v54
	v_mul_f32_e32 v55, v74, v55
	v_mul_f32_e32 v38, v73, v38
	v_mul_f32_e32 v39, v73, v39
	v_mul_f32_e32 v22, v72, v22
	v_mul_f32_e32 v23, v72, v23
	v_mul_f32_e32 v6, v71, v6
	v_mul_f32_e32 v7, v71, v7
	v_lshl_add_u64 v[68:69], v[66:67], 0, v[160:161]
	v_cvt_pk_bf16_f32 v114, v54, v55
	v_cvt_pk_bf16_f32 v116, v38, v39
	v_cvt_pk_bf16_f32 v118, v22, v23
	v_cvt_pk_bf16_f32 v120, v6, v7
	v_mov_b32_dpp v115, v114 quad_perm:[1,0,3,2] row_mask:0xf bank_mask:0xf bound_ctrl:1
	v_mov_b32_dpp v117, v116 quad_perm:[1,0,3,2] row_mask:0xf bank_mask:0xf bound_ctrl:1
	v_mov_b32_dpp v119, v118 quad_perm:[1,0,3,2] row_mask:0xf bank_mask:0xf bound_ctrl:1
	v_mov_b32_dpp v121, v120 quad_perm:[1,0,3,2] row_mask:0xf bank_mask:0xf bound_ctrl:1
	v_perm_b32 v115, v115, v114, v76
	global_store_dword v[68:69], v115, off
	v_perm_b32 v117, v117, v116, v76
	global_store_dword v[68:69], v117, off offset:64
	v_perm_b32 v119, v119, v118, v76
	global_store_dword v[68:69], v119, off offset:128
	v_perm_b32 v121, v121, v120, v76
	global_store_dword v[68:69], v121, off offset:192
	v_mul_f32_e32 v56, v56, v86
	v_mul_f32_e32 v57, v57, v87
	v_mul_f32_e32 v40, v40, v86
	v_mul_f32_e32 v41, v41, v87
	v_mul_f32_e32 v24, v24, v86
	v_mul_f32_e32 v25, v25, v87
	v_mul_f32_e32 v8, v8, v86
	v_mul_f32_e32 v9, v9, v87
	v_mul_f32_e32 v56, v74, v56
	v_mul_f32_e32 v57, v74, v57
	v_mul_f32_e32 v40, v73, v40
	v_mul_f32_e32 v41, v73, v41
	v_mul_f32_e32 v24, v72, v24
	v_mul_f32_e32 v25, v72, v25
	v_mul_f32_e32 v8, v71, v8
	v_mul_f32_e32 v9, v71, v9
	v_lshl_add_u64 v[68:69], v[66:67], 0, v[164:165]
	v_cvt_pk_bf16_f32 v122, v56, v57
	v_cvt_pk_bf16_f32 v124, v40, v41
	v_cvt_pk_bf16_f32 v126, v24, v25
	v_cvt_pk_bf16_f32 v128, v8, v9
	v_mov_b32_dpp v123, v122 quad_perm:[1,0,3,2] row_mask:0xf bank_mask:0xf bound_ctrl:1
	v_mov_b32_dpp v125, v124 quad_perm:[1,0,3,2] row_mask:0xf bank_mask:0xf bound_ctrl:1
	v_mov_b32_dpp v127, v126 quad_perm:[1,0,3,2] row_mask:0xf bank_mask:0xf bound_ctrl:1
	v_mov_b32_dpp v129, v128 quad_perm:[1,0,3,2] row_mask:0xf bank_mask:0xf bound_ctrl:1
	v_perm_b32 v123, v123, v122, v76
	global_store_dword v[68:69], v123, off
	v_perm_b32 v125, v125, v124, v76
	global_store_dword v[68:69], v125, off offset:64
	v_perm_b32 v127, v127, v126, v76
	global_store_dword v[68:69], v127, off offset:128
	v_perm_b32 v129, v129, v128, v76
	global_store_dword v[68:69], v129, off offset:192
	v_mul_f32_e32 v58, v58, v88
	v_mul_f32_e32 v59, v59, v89
	v_mul_f32_e32 v42, v42, v88
	v_mul_f32_e32 v43, v43, v89
	v_mul_f32_e32 v26, v26, v88
	v_mul_f32_e32 v27, v27, v89
	v_mul_f32_e32 v10, v10, v88
	v_mul_f32_e32 v11, v11, v89
	v_mul_f32_e32 v58, v74, v58
	v_mul_f32_e32 v59, v74, v59
	v_mul_f32_e32 v42, v73, v42
	v_mul_f32_e32 v43, v73, v43
	v_mul_f32_e32 v26, v72, v26
	v_mul_f32_e32 v27, v72, v27
	v_mul_f32_e32 v10, v71, v10
	v_mul_f32_e32 v11, v71, v11
	v_lshl_add_u64 v[68:69], v[66:67], 0, v[168:169]
	v_cvt_pk_bf16_f32 v114, v58, v59
	v_cvt_pk_bf16_f32 v116, v42, v43
	v_cvt_pk_bf16_f32 v118, v26, v27
	v_cvt_pk_bf16_f32 v120, v10, v11
	v_mov_b32_dpp v115, v114 quad_perm:[1,0,3,2] row_mask:0xf bank_mask:0xf bound_ctrl:1
	v_mov_b32_dpp v117, v116 quad_perm:[1,0,3,2] row_mask:0xf bank_mask:0xf bound_ctrl:1
	v_mov_b32_dpp v119, v118 quad_perm:[1,0,3,2] row_mask:0xf bank_mask:0xf bound_ctrl:1
	v_mov_b32_dpp v121, v120 quad_perm:[1,0,3,2] row_mask:0xf bank_mask:0xf bound_ctrl:1
	v_perm_b32 v115, v115, v114, v76
	global_store_dword v[68:69], v115, off
	v_perm_b32 v117, v117, v116, v76
	global_store_dword v[68:69], v117, off offset:64
	v_perm_b32 v119, v119, v118, v76
	global_store_dword v[68:69], v119, off offset:128
	v_perm_b32 v121, v121, v120, v76
	global_store_dword v[68:69], v121, off offset:192
	v_mul_f32_e32 v60, v60, v90
	v_mul_f32_e32 v61, v61, v91
	v_mul_f32_e32 v44, v44, v90
	v_mul_f32_e32 v45, v45, v91
	v_mul_f32_e32 v28, v28, v90
	v_mul_f32_e32 v29, v29, v91
	v_mul_f32_e32 v12, v12, v90
	v_mul_f32_e32 v13, v13, v91
	v_mul_f32_e32 v60, v74, v60
	v_mul_f32_e32 v61, v74, v61
	v_mul_f32_e32 v44, v73, v44
	v_mul_f32_e32 v45, v73, v45
	v_mul_f32_e32 v28, v72, v28
	v_mul_f32_e32 v29, v72, v29
	v_mul_f32_e32 v12, v71, v12
	v_mul_f32_e32 v13, v71, v13
	v_lshl_add_u64 v[68:69], v[66:67], 0, v[172:173]
	v_cvt_pk_bf16_f32 v122, v60, v61
	v_cvt_pk_bf16_f32 v124, v44, v45
	v_cvt_pk_bf16_f32 v126, v28, v29
	v_cvt_pk_bf16_f32 v128, v12, v13
	v_mov_b32_dpp v123, v122 quad_perm:[1,0,3,2] row_mask:0xf bank_mask:0xf bound_ctrl:1
	v_mov_b32_dpp v125, v124 quad_perm:[1,0,3,2] row_mask:0xf bank_mask:0xf bound_ctrl:1
	v_mov_b32_dpp v127, v126 quad_perm:[1,0,3,2] row_mask:0xf bank_mask:0xf bound_ctrl:1
	v_mov_b32_dpp v129, v128 quad_perm:[1,0,3,2] row_mask:0xf bank_mask:0xf bound_ctrl:1
	v_perm_b32 v123, v123, v122, v76
	global_store_dword v[68:69], v123, off
	v_perm_b32 v125, v125, v124, v76
	global_store_dword v[68:69], v125, off offset:64
	v_perm_b32 v127, v127, v126, v76
	global_store_dword v[68:69], v127, off offset:128
	v_perm_b32 v129, v129, v128, v76
	global_store_dword v[68:69], v129, off offset:192
	v_mul_f32_e32 v62, v62, v92
	v_mul_f32_e32 v63, v63, v93
	v_mul_f32_e32 v46, v46, v92
	v_mul_f32_e32 v47, v47, v93
	v_mul_f32_e32 v30, v30, v92
	v_mul_f32_e32 v31, v31, v93
	v_mul_f32_e32 v14, v14, v92
	v_mul_f32_e32 v15, v15, v93
	v_mul_f32_e32 v62, v74, v62
	v_mul_f32_e32 v63, v74, v63
	v_mul_f32_e32 v46, v73, v46
	v_mul_f32_e32 v47, v73, v47
	v_mul_f32_e32 v30, v72, v30
	v_mul_f32_e32 v31, v72, v31
	v_mul_f32_e32 v14, v71, v14
	v_mul_f32_e32 v15, v71, v15
	v_lshl_add_u64 v[68:69], v[66:67], 0, v[176:177]
	v_cvt_pk_bf16_f32 v114, v62, v63
	v_cvt_pk_bf16_f32 v116, v46, v47
	v_cvt_pk_bf16_f32 v118, v30, v31
	v_cvt_pk_bf16_f32 v120, v14, v15
	v_mov_b32_dpp v115, v114 quad_perm:[1,0,3,2] row_mask:0xf bank_mask:0xf bound_ctrl:1
	v_mov_b32_dpp v117, v116 quad_perm:[1,0,3,2] row_mask:0xf bank_mask:0xf bound_ctrl:1
	v_mov_b32_dpp v119, v118 quad_perm:[1,0,3,2] row_mask:0xf bank_mask:0xf bound_ctrl:1
	v_mov_b32_dpp v121, v120 quad_perm:[1,0,3,2] row_mask:0xf bank_mask:0xf bound_ctrl:1
	v_perm_b32 v115, v115, v114, v76
	global_store_dword v[68:69], v115, off
	v_perm_b32 v117, v117, v116, v76
	global_store_dword v[68:69], v117, off offset:64
	v_perm_b32 v119, v119, v118, v76
	global_store_dword v[68:69], v119, off offset:128
	v_perm_b32 v121, v121, v120, v76
	global_store_dword v[68:69], v121, off offset:192
	v_mul_f32_e32 v64, v64, v94
	v_mul_f32_e32 v65, v65, v95
	v_mul_f32_e32 v48, v48, v94
	v_mul_f32_e32 v49, v49, v95
	v_mul_f32_e32 v32, v32, v94
	v_mul_f32_e32 v33, v33, v95
	v_mul_f32_e32 v16, v16, v94
	v_mul_f32_e32 v17, v17, v95
	v_mul_f32_e32 v64, v74, v64
	v_mul_f32_e32 v65, v74, v65
	v_mul_f32_e32 v48, v73, v48
	v_mul_f32_e32 v49, v73, v49
	v_mul_f32_e32 v32, v72, v32
	v_mul_f32_e32 v33, v72, v33
	v_mul_f32_e32 v16, v71, v16
	v_mul_f32_e32 v17, v71, v17
	v_lshl_add_u64 v[68:69], v[66:67], 0, v[180:181]
	v_cvt_pk_bf16_f32 v122, v64, v65
	v_cvt_pk_bf16_f32 v124, v48, v49
	v_cvt_pk_bf16_f32 v126, v32, v33
	v_cvt_pk_bf16_f32 v128, v16, v17
	v_mov_b32_dpp v123, v122 quad_perm:[1,0,3,2] row_mask:0xf bank_mask:0xf bound_ctrl:1
	v_mov_b32_dpp v125, v124 quad_perm:[1,0,3,2] row_mask:0xf bank_mask:0xf bound_ctrl:1
	v_mov_b32_dpp v127, v126 quad_perm:[1,0,3,2] row_mask:0xf bank_mask:0xf bound_ctrl:1
	v_mov_b32_dpp v129, v128 quad_perm:[1,0,3,2] row_mask:0xf bank_mask:0xf bound_ctrl:1
	v_perm_b32 v123, v123, v122, v76
	global_store_dword v[68:69], v123, off
	v_perm_b32 v125, v125, v124, v76
	global_store_dword v[68:69], v125, off offset:64
	v_perm_b32 v127, v127, v126, v76
	global_store_dword v[68:69], v127, off offset:128
	v_perm_b32 v129, v129, v128, v76
	global_store_dword v[68:69], v129, off offset:192
.LBB0_883:
	s_or_b64 exec, exec, s[0:1]
	s_and_saveexec_b64 s[0:1], s[88:89]
	s_cbranch_execz .LBB0_726
	s_waitcnt vmcnt(20)
	v_mov_b32_e32 v0, s85
	ds_write_b32 v0, v70
	s_branch .LBB0_726
.LBB0_885:
	v_mov_b32_e32 v17, 0
	v_mov_b32_e32 v16, 0
	v_mov_b32_e32 v15, 0
	v_mov_b32_e32 v14, 0
	v_mov_b32_e32 v13, 0
	v_mov_b32_e32 v12, 0
	v_mov_b32_e32 v11, 0
	v_mov_b32_e32 v10, 0
	v_mov_b32_e32 v9, 0
	v_mov_b32_e32 v8, 0
	v_mov_b32_e32 v7, 0
	v_mov_b32_e32 v6, 0
	v_mov_b32_e32 v5, 0
	v_mov_b32_e32 v4, 0
	v_mov_b32_e32 v3, 0
	v_mov_b32_e32 v2, 0
	v_mov_b32_e32 v33, 0
	v_mov_b32_e32 v32, 0
	v_mov_b32_e32 v31, 0
	v_mov_b32_e32 v30, 0
	v_mov_b32_e32 v29, 0
	v_mov_b32_e32 v28, 0
	v_mov_b32_e32 v27, 0
	v_mov_b32_e32 v26, 0
	v_mov_b32_e32 v25, 0
	v_mov_b32_e32 v24, 0
	v_mov_b32_e32 v23, 0
	v_mov_b32_e32 v22, 0
	v_mov_b32_e32 v21, 0
	v_mov_b32_e32 v20, 0
	v_mov_b32_e32 v19, 0
	v_mov_b32_e32 v18, 0
	v_mov_b32_e32 v49, 0
	v_mov_b32_e32 v48, 0
	v_mov_b32_e32 v47, 0
	v_mov_b32_e32 v46, 0
	v_mov_b32_e32 v45, 0
	v_mov_b32_e32 v44, 0
	v_mov_b32_e32 v43, 0
	v_mov_b32_e32 v42, 0
	v_mov_b32_e32 v41, 0
	v_mov_b32_e32 v40, 0
	v_mov_b32_e32 v39, 0
	v_mov_b32_e32 v38, 0
	v_mov_b32_e32 v37, 0
	v_mov_b32_e32 v36, 0
	v_mov_b32_e32 v35, 0
	v_mov_b32_e32 v34, 0
	v_mov_b32_e32 v65, 0
	v_mov_b32_e32 v64, 0
	v_mov_b32_e32 v63, 0
	v_mov_b32_e32 v62, 0
	v_mov_b32_e32 v61, 0
	v_mov_b32_e32 v60, 0
	v_mov_b32_e32 v59, 0
	v_mov_b32_e32 v58, 0
	v_mov_b32_e32 v57, 0
	v_mov_b32_e32 v56, 0
	v_mov_b32_e32 v55, 0
	v_mov_b32_e32 v54, 0
	v_mov_b32_e32 v53, 0
	v_mov_b32_e32 v52, 0
	v_mov_b32_e32 v51, 0
	v_mov_b32_e32 v50, 0
	v_mov_b32_e32 v219, 0
	v_mov_b32_e32 v70, 0
	s_lshl_b32 s0, s58, 7
	s_and_b32 s4, s0, 0x180
	v_readlane_b32 s16, v254, 16
	v_readlane_b32 s17, v254, 17
	v_or_b32_e32 v75, s4, v136
	v_lshlrev_b32_e32 v75, 2, v75
	s_nop 4
	global_load_dword v74, v75, s[16:17]
	global_load_dword v73, v75, s[16:17] offset:128
	global_load_dword v72, v75, s[16:17] offset:256
	global_load_dword v71, v75, s[16:17] offset:384
	s_and_saveexec_b64 s[0:1], s[88:89]
	s_cbranch_execz .LBB0_753
.LBB0_886:
	s_mov_b64 s[10:11], exec
	v_mbcnt_lo_u32_b32 v0, s10, 0
	v_mbcnt_hi_u32_b32 v0, s11, v0
	v_cmp_eq_u32_e32 vcc, 0, v0
	s_and_saveexec_b64 s[4:5], vcc
	s_cbranch_execz .LBB0_888
	s_bcnt1_i32_b64 s10, s[10:11]
	v_mov_b32_e32 v66, s10
	v_readlane_b32 s10, v255, 50
	v_readlane_b32 s11, v255, 51
	s_nop 4
	global_atomic_add v70, v1, v66, s[10:11] sc0
.LBB0_888:
	s_or_b64 exec, exec, s[4:5]
	s_or_b64 exec, exec, s[0:1]
	s_and_saveexec_b64 s[0:1], s[6:7]
	s_cbranch_execnz .LBB0_754
	s_branch .LBB0_755
